# baseline (speedup 1.0000x reference)
; #define SBAR() __builtin_amdgcn_sched_barrier(0)
; template <int MODE>
; __device__ __forceinline__ void qkt(f32x16& p0, f32x16& p1, const int (&ka)[4], const int (&kra)[4], const bf16x8* qr) {
;     ...
;         KRD(kb0[0], ka[0], 0); KRD(kb1[0], ka[0], 8192); KRD(kb0[1], ka[1], 0); KRD(kb1[1], ka[1], 8192);
;         KRD(kb0[2], ka[2], 0); KRD(kb1[2], ka[2], 8192); asm volatile("s_waitcnt lgkmcnt(4)" ::: "memory"); SBAR(); p0 = __builtin_amdgcn_mfma_f32_32x32x16_bf16(kb0[0], qr[0], zz, 0, 0, 0); p1 = __builtin_amdgcn_mfma_f32_32x32x16_bf16(kb1[0], qr[0], zz, 0, 0, 0);
;         KRD(kb0[0], ka[3], 0); KRD(kb1[0], ka[3], 8192); asm volatile("s_waitcnt lgkmcnt(4)" ::: "memory"); SBAR(); p0 = __builtin_amdgcn_mfma_f32_32x32x16_bf16(kb0[1], qr[1], p0, 0, 0, 0); p1 = __builtin_amdgcn_mfma_f32_32x32x16_bf16(kb1[1], qr[1], p1, 0, 0, 0);
;         KRD(kb0[1], ka[0], 128); KRD(kb1[1], ka[0], 8320); asm volatile("s_waitcnt lgkmcnt(4)" ::: "memory"); SBAR(); p0 = __builtin_amdgcn_mfma_f32_32x32x16_bf16(kb0[2], qr[2], p0, 0, 0, 0); p1 = __builtin_amdgcn_mfma_f32_32x32x16_bf16(kb1[2], qr[2], p1, 0, 0, 0);
;         KRD(kb0[2], ka[1], 128); KRD(kb1[2], ka[1], 8320); asm volatile("s_waitcnt lgkmcnt(4)" ::: "memory"); SBAR(); p0 = __builtin_amdgcn_mfma_f32_32x32x16_bf16(kb0[0], qr[3], p0, 0, 0, 0); p1 = __builtin_amdgcn_mfma_f32_32x32x16_bf16(kb1[0], qr[3], p1, 0, 0, 0);
;         KRD(kb0[0], ka[2], 128); KRD(kb1[0], ka[2], 8320); asm volatile("s_waitcnt lgkmcnt(4)" ::: "memory"); SBAR(); p0 = __builtin_amdgcn_mfma_f32_32x32x16_bf16(kb0[1], qr[4], p0, 0, 0, 0); p1 = __builtin_amdgcn_mfma_f32_32x32x16_bf16(kb1[1], qr[4], p1, 0, 0, 0);
;         KRD(kb0[1], ka[3], 128); KRD(kb1[1], ka[3], 8320); asm volatile("s_waitcnt lgkmcnt(4)" ::: "memory"); SBAR(); p0 = __builtin_amdgcn_mfma_f32_32x32x16_bf16(kb0[2], qr[5], p0, 0, 0, 0); p1 = __builtin_amdgcn_mfma_f32_32x32x16_bf16(kb1[2], qr[5], p1, 0, 0, 0);
;         asm volatile("s_waitcnt lgkmcnt(2)" ::: "memory"); SBAR(); p0 = __builtin_amdgcn_mfma_f32_32x32x16_bf16(kb0[0], qr[6], p0, 0, 0, 0); p1 = __builtin_amdgcn_mfma_f32_32x32x16_bf16(kb1[0], qr[6], p1, 0, 0, 0);
;         asm volatile("s_waitcnt lgkmcnt(0)" ::: "memory"); SBAR(); p0 = __builtin_amdgcn_mfma_f32_32x32x16_bf16(kb0[1], qr[7], p0, 0, 0, 0); p1 = __builtin_amdgcn_mfma_f32_32x32x16_bf16(kb1[1], qr[7], p1, 0, 0, 0);
.LBB0_252:
	v_and_b32_e32 v171, 63, v68
	v_lshlrev_b32_e32 v17, 4, v171
	v_lshlrev_b32_e32 v16, 3, v171
	v_and_b32_e32 v17, 0xc0, v17
	v_lshlrev_b32_e32 v18, 1, v171
	v_and_or_b32 v17, v16, 24, v17
	v_and_b32_e32 v18, 32, v18
	v_and_b32_e32 v16, 0x100, v16
	v_or3_b32 v16, v17, v18, v16
	v_lshlrev_b32_e32 v172, 4, v166
	v_lshlrev_b32_e32 v17, 4, v68
	v_add_u32_e32 v173, 0, v16
	v_lshl_add_u32 v16, v165, 8, s2
	v_and_b32_e32 v17, 0x70, v17
	v_or_b32_e32 v18, 32, v172
	v_xad_u32 v175, v18, v17, v16
	v_or_b32_e32 v18, 64, v172
	v_xad_u32 v176, v18, v17, v16
	v_or_b32_e32 v18, 0x60, v172
	v_xad_u32 v174, v172, v17, v16
	v_xad_u32 v177, v18, v17, v16
	ds_read_b128 v[16:19], v174 offset:0
	ds_read_b128 v[20:23], v174 offset:0x2000
	ds_read_b128 v[72:75], v175 offset:0
	ds_read_b128 v[76:79], v175 offset:0x2000
	ds_read_b128 v[80:83], v176 offset:0
	s_and_b32 s0, s26, 0x3fffffc0
	ds_read_b128 v[84:87], v176 offset:0x2000
	s_lshl_b32 s0, s0, 2
	s_waitcnt lgkmcnt(4)
	s_add_i32 s26, s0, 0
	s_add_i32 s26, s26, 0x22000
	v_mov_b32_e32 v1, v0
	v_mov_b32_e32 v2, v0
	v_mov_b32_e32 v3, v0
	v_mov_b32_e32 v4, v0
	v_mov_b32_e32 v5, v0
	v_mov_b32_e32 v6, v0
	v_mov_b32_e32 v7, v0
	v_mov_b32_e32 v8, v0
	v_mov_b32_e32 v9, v0
	v_mov_b32_e32 v10, v0
	v_mov_b32_e32 v11, v0
	v_mov_b32_e32 v12, v0
	v_mov_b32_e32 v13, v0
	v_mov_b32_e32 v14, v0
	v_mov_b32_e32 v15, v0
	s_mov_b32 s0, 3
	s_mov_b32 s27, 4
	s_mov_b32 s28, 1
	v_mfma_f32_32x32x16_bf16 v[32:47], v[16:19], v[96:99], 0
	ds_read_b128 v[88:91], v177 offset:0
	ds_read_b128 v[92:95], v177 offset:0x2000
	s_waitcnt lgkmcnt(4)
	v_mfma_f32_32x32x16_bf16 v[16:31], v[20:23], v[96:99], 0
	v_mfma_f32_32x32x16_bf16 v[32:47], v[72:75], v[112:115], v[32:47]
	ds_read_b128 v[72:75], v174 offset:0x80
	v_mfma_f32_32x32x16_bf16 v[16:31], v[76:79], v[112:115], v[16:31]
	ds_read_b128 v[76:79], v174 offset:0x2080
	s_waitcnt lgkmcnt(4)
	v_mfma_f32_32x32x16_bf16 v[32:47], v[80:83], v[100:103], v[32:47]
	ds_read_b128 v[80:83], v175 offset:0x80
	v_mfma_f32_32x32x16_bf16 v[16:31], v[84:87], v[100:103], v[16:31]
	ds_read_b128 v[84:87], v175 offset:0x2080
	s_waitcnt lgkmcnt(4)
	v_mfma_f32_32x32x16_bf16 v[32:47], v[88:91], v[116:119], v[32:47]
	ds_read_b128 v[88:91], v176 offset:0x80
	v_mfma_f32_32x32x16_bf16 v[16:31], v[92:95], v[116:119], v[16:31]
	ds_read_b128 v[92:95], v176 offset:0x2080
	s_waitcnt lgkmcnt(4)
	v_mfma_f32_32x32x16_bf16 v[32:47], v[72:75], v[104:107], v[32:47]
	ds_read_b128 v[72:75], v177 offset:0x80
	v_mfma_f32_32x32x16_bf16 v[16:31], v[76:79], v[104:107], v[16:31]
	ds_read_b128 v[76:79], v177 offset:0x2080
	s_waitcnt lgkmcnt(4)
	v_mfma_f32_32x32x16_bf16 v[32:47], v[80:83], v[120:123], v[32:47]
	s_waitcnt lgkmcnt(2)
	v_mfma_f32_32x32x16_bf16 v[16:31], v[84:87], v[120:123], v[16:31]
	v_mfma_f32_32x32x16_bf16 v[32:47], v[88:91], v[108:111], v[32:47]
	s_waitcnt lgkmcnt(0)
	v_mfma_f32_32x32x16_bf16 v[16:31], v[92:95], v[108:111], v[16:31]
	v_mfma_f32_32x32x16_bf16 v[32:47], v[72:75], v[124:127], v[32:47]
	s_barrier
	v_cmp_gt_u32_e64 s[6:7], 32, v171
	v_lshl_add_u32 v179, v165, 2, s26
	s_mov_b32 s33, 0
	s_mov_b32 s31, 0
	s_nop 6
	v_max_f32_e32 v68, v33, v33
	v_max_f32_e32 v71, v32, v32
	v_mfma_f32_32x32x16_bf16 v[16:31], v[76:79], v[124:127], v[16:31]
	v_max_f32_e32 v68, v71, v68
	v_max3_f32 v68, v68, v34, v35
	v_max3_f32 v68, v68, v36, v37
	v_max3_f32 v68, v68, v38, v39
	v_max3_f32 v68, v68, v40, v41
	v_max3_f32 v68, v68, v42, v43
	v_max3_f32 v68, v68, v44, v45
	v_max3_f32 v68, v68, v46, v47
	s_nop 3
	v_max3_f32 v68, v68, v16, v17
	v_max3_f32 v68, v68, v18, v19
	v_max3_f32 v68, v68, v20, v21
	v_max3_f32 v68, v68, v22, v23
	v_max3_f32 v68, v68, v24, v25
	v_max3_f32 v68, v68, v26, v27
	v_max3_f32 v68, v68, v28, v29
	v_max3_f32 v68, v68, v30, v31
	v_mov_b32_e32 v71, v68
	s_nop 1
	v_permlane32_swap_b32_e32 v68, v71
	v_max_f32_e32 v71, v71, v71
	v_max_f32_e32 v68, v68, v68
	v_max_f32_e32 v68, v68, v71
	v_add_f32_e32 v71, 0x46ea6000, v68
	v_cmp_ge_f32_e32 vcc, s91, v71
	s_cmp_eq_u64 vcc, exec
	s_cselect_b64 vcc, -1, 0
	v_max_f32_e32 v68, 0xc6ea6000, v68
	v_cndmask_b32_e32 v178, v68, v193, vcc
	v_mul_f32_e32 v71, 0xbe0293ee, v178
	v_fmamk_f32 v32, v32, 0x3e0293ee, v71
	v_fmamk_f32 v33, v33, 0x3e0293ee, v71
	v_fmamk_f32 v34, v34, 0x3e0293ee, v71
	v_fmamk_f32 v35, v35, 0x3e0293ee, v71
	v_fmamk_f32 v36, v36, 0x3e0293ee, v71
	v_fmamk_f32 v37, v37, 0x3e0293ee, v71
	v_fmamk_f32 v38, v38, 0x3e0293ee, v71
	v_fmamk_f32 v39, v39, 0x3e0293ee, v71
	v_fmamk_f32 v40, v40, 0x3e0293ee, v71
	v_fmamk_f32 v41, v41, 0x3e0293ee, v71
	v_fmamk_f32 v42, v42, 0x3e0293ee, v71
	v_fmamk_f32 v43, v43, 0x3e0293ee, v71
	v_fmamk_f32 v44, v44, 0x3e0293ee, v71
	v_fmamk_f32 v45, v45, 0x3e0293ee, v71
	v_fmamk_f32 v46, v46, 0x3e0293ee, v71
	v_fmamk_f32 v47, v47, 0x3e0293ee, v71
	v_fmamk_f32 v16, v16, 0x3e0293ee, v71
	v_fmamk_f32 v17, v17, 0x3e0293ee, v71
	v_fmamk_f32 v18, v18, 0x3e0293ee, v71
	v_fmamk_f32 v19, v19, 0x3e0293ee, v71
	v_fmamk_f32 v20, v20, 0x3e0293ee, v71
	v_fmamk_f32 v21, v21, 0x3e0293ee, v71
	v_fmamk_f32 v22, v22, 0x3e0293ee, v71
	v_fmamk_f32 v23, v23, 0x3e0293ee, v71
	v_fmamk_f32 v24, v24, 0x3e0293ee, v71
	v_fmamk_f32 v25, v25, 0x3e0293ee, v71
; #define SLOAD(k0) SLOADX(sg, k0)
; __device__ __forceinline__ void finishSM(f32x16& p0, f32x16& p1, float alpha, float& l_reg, bf16x8& pa0, bf16x8& pa1, bf16x8& pa2, bf16x8& pa3) {
;     ...
;     for (int r = 0; r < 16; ++r) p1[r] = __builtin_amdgcn_exp2f(p1[r]);
;     float ps = 0;
; #pragma unroll
;     for (int r = 0; r < 16; ++r) ps += p0[r];
; #pragma unroll
;     for (int r = 0; r < 16; ++r) ps += p1[r];
;     { auto rr = __builtin_amdgcn_permlane32_swap(__float_as_uint(ps), __float_as_uint(ps), false, false);
;       ps = __uint_as_float(rr[0]) + __uint_as_float(rr[1]); }
;     l_reg = l_reg * alpha + ps;
;     ...
;     PK4(p0, 0, pa0); PK4(p0, 8, pa1); PK4(p1, 0, pa2); PK4(p1, 8, pa3);
; template <int MODE> ...
;     ...
;     if (2 < NT) { asm volatile("s_waitcnt vmcnt(0)" ::: "memory"); SWRITEX(sg, 2, 2); } if (3 < NT) SLOAD(3 * 64);
	v_fmamk_f32 v26, v26, 0x3e0293ee, v71
	v_fmamk_f32 v27, v27, 0x3e0293ee, v71
	v_fmamk_f32 v28, v28, 0x3e0293ee, v71
	v_fmamk_f32 v29, v29, 0x3e0293ee, v71
	v_fmamk_f32 v30, v30, 0x3e0293ee, v71
	v_fmac_f32_e32 v71, 0x3e0293ee, v31
	v_exp_f32_e32 v31, v32
	v_exp_f32_e32 v32, v33
	v_exp_f32_e32 v33, v34
	v_exp_f32_e32 v34, v35
	v_exp_f32_e32 v35, v36
	v_exp_f32_e32 v36, v37
	v_exp_f32_e32 v37, v38
	v_exp_f32_e32 v38, v39
	v_exp_f32_e32 v39, v40
	v_exp_f32_e32 v40, v41
	v_exp_f32_e32 v41, v42
	v_exp_f32_e32 v42, v43
	v_exp_f32_e32 v43, v44
	v_exp_f32_e32 v44, v45
	v_exp_f32_e32 v45, v46
	v_exp_f32_e32 v46, v47
	v_exp_f32_e32 v47, v71
	v_add_f32_e32 v71, 0, v31
	v_add_f32_e32 v71, v32, v71
	v_add_f32_e32 v71, v33, v71
	v_add_f32_e32 v71, v34, v71
	v_add_f32_e32 v71, v35, v71
	v_add_f32_e32 v71, v36, v71
	v_add_f32_e32 v71, v37, v71
	v_add_f32_e32 v71, v38, v71
	v_add_f32_e32 v71, v39, v71
	v_add_f32_e32 v71, v40, v71
	v_add_f32_e32 v71, v41, v71
	v_add_f32_e32 v71, v42, v71
	v_exp_f32_e32 v16, v16
	v_add_f32_e32 v71, v43, v71
	v_add_f32_e32 v71, v44, v71
	v_add_f32_e32 v71, v45, v71
	v_exp_f32_e32 v17, v17
	v_add_f32_e32 v71, v46, v71
	s_add_i32 s2, 0, 0x18000
	v_add_f32_e32 v71, v16, v71
	v_cvt_pk_bf16_f32 v144, v31, v32
	v_cvt_pk_bf16_f32 v145, v33, v34
	v_cvt_pk_bf16_f32 v146, v35, v36
	v_cvt_pk_bf16_f32 v147, v37, v38
	v_cvt_pk_bf16_f32 v148, v39, v40
	v_cvt_pk_bf16_f32 v149, v41, v42
	v_cvt_pk_bf16_f32 v150, v43, v44
	v_cvt_pk_bf16_f32 v151, v45, v46
	v_cvt_pk_bf16_f32 v152, v16, v17
	v_add_u32_e32 v16, s2, v169
	v_exp_f32_e32 v18, v18
	v_exp_f32_e32 v19, v19
	v_exp_f32_e32 v20, v20
	v_exp_f32_e32 v21, v21
	v_exp_f32_e32 v22, v22
	v_exp_f32_e32 v23, v23
	v_exp_f32_e32 v24, v24
	v_exp_f32_e32 v25, v25
	v_exp_f32_e32 v26, v26
	v_exp_f32_e32 v27, v27
	v_exp_f32_e32 v28, v28
	v_exp_f32_e32 v29, v29
	v_exp_f32_e32 v30, v30
	v_cvt_pk_bf16_f32 v153, v18, v19
	v_cvt_pk_bf16_f32 v154, v20, v21
	v_cvt_pk_bf16_f32 v155, v22, v23
	v_cvt_pk_bf16_f32 v156, v24, v25
	v_cvt_pk_bf16_f32 v157, v26, v27
	v_cvt_pk_bf16_f32 v158, v28, v29
	v_cvt_pk_bf16_f32 v159, v30, v47
	s_waitcnt vmcnt(0)
	s_waitcnt vmcnt(3)
	ds_write_b128 v69, v[48:51] offset:32768
	s_waitcnt vmcnt(2)
	ds_write_b128 v70, v[56:59] offset:32768
	s_waitcnt vmcnt(1)
	ds_write_b128 v16, v[52:55]
	v_add_u32_e32 v16, s2, v170
	s_add_u32 s2, s8, 0x1e0000
	s_addc_u32 s3, s9, 0
	v_add_f32_e32 v71, v17, v71
	s_waitcnt vmcnt(0)
	ds_write_b128 v16, v[60:63]
	v_lshl_add_u64 v[16:17], s[2:3], 0, v[66:67]
	global_load_dwordx4 v[128:131], v[16:17], off
	v_lshl_add_u64 v[16:17], s[2:3], 0, v[64:65]
	s_add_u32 s2, s8, 0x1e0400
	s_addc_u32 s3, s9, 0
	global_load_dwordx4 v[132:135], v[16:17], off
	v_lshl_add_u64 v[16:17], s[2:3], 0, v[66:67]
	global_load_dwordx4 v[136:139], v[16:17], off
	v_lshl_add_u64 v[16:17], s[2:3], 0, v[64:65]
	global_load_dwordx4 v[140:143], v[16:17], off
	v_add_f32_e32 v71, v18, v71
	v_add_f32_e32 v71, v19, v71
	v_add_f32_e32 v71, v20, v71
	v_add_f32_e32 v71, v21, v71
	v_add_f32_e32 v71, v22, v71
	v_add_f32_e32 v71, v23, v71
	v_add_f32_e32 v71, v24, v71
	v_add_f32_e32 v71, v25, v71
	v_add_f32_e32 v71, v26, v71
	v_add_f32_e32 v71, v27, v71
	v_sub_f32_e32 v17, 0xc6ea6000, v68
	v_add_f32_e32 v71, v28, v71
	v_mul_f32_e32 v17, 0x3e0293ee, v17
	v_add_f32_e32 v71, v29, v71
	v_exp_f32_e32 v17, v17
	s_mul_i32 s2, s24, 0xa0000
	v_add_f32_e32 v71, v30, v71
	s_add_i32 s2, s2, 0xffc00000
	s_lshr_b32 s94, s4, 2
	v_add_f32_e32 v71, v47, v71
	s_add_u32 s30, s2, 0x360000
	s_mul_hi_u32 s8, s5, 0x2800
	s_mulk_i32 s5, 0x2800
	s_lshl_b64 s[2:3], s[94:95], 8
	v_mov_b32_e32 v72, v71
	s_add_u32 s2, s5, s2
	s_nop 0
	v_permlane32_swap_b32_e32 v71, v72
	v_mul_f32_e32 v17, 0, v17
	s_addc_u32 s3, s8, s3
	v_add_f32_e32 v16, v71, v72
	v_cndmask_b32_e64 v17, v17, 0, vcc
	s_add_u32 s2, s80, s2
	v_add_f32_e32 v180, v16, v17
	s_addc_u32 s3, s81, s3
	v_mov_b64_e32 v[62:63], v[14:15]
	v_mov_b64_e32 v[46:47], v[14:15]
	v_mov_b64_e32 v[30:31], v[14:15]
	v_permlane32_swap_b32_e32 v144, v146
	v_permlane32_swap_b32_e32 v145, v147
	v_permlane32_swap_b32_e32 v148, v150
	v_permlane32_swap_b32_e32 v149, v151
	v_permlane32_swap_b32_e32 v152, v154
	v_permlane32_swap_b32_e32 v153, v155
	v_permlane32_swap_b32_e32 v156, v158
	v_permlane32_swap_b32_e32 v157, v159
	v_lshl_add_u64 v[160:161], s[2:3], 0, v[66:67]
	v_lshl_add_u64 v[162:163], s[2:3], 0, v[64:65]
	s_mov_b64 s[2:3], 0
	v_mov_b64_e32 v[60:61], v[12:13]
	v_mov_b64_e32 v[58:59], v[10:11]
	v_mov_b64_e32 v[56:57], v[8:9]
	v_mov_b64_e32 v[54:55], v[6:7]
	v_mov_b64_e32 v[52:53], v[4:5]
	v_mov_b64_e32 v[50:51], v[2:3]
	v_mov_b64_e32 v[48:49], v[0:1]
	v_mov_b64_e32 v[44:45], v[12:13]
	v_mov_b64_e32 v[42:43], v[10:11]
	v_mov_b64_e32 v[40:41], v[8:9]
	v_mov_b64_e32 v[38:39], v[6:7]
	v_mov_b64_e32 v[36:37], v[4:5]
	v_mov_b64_e32 v[34:35], v[2:3]
	v_mov_b64_e32 v[32:33], v[0:1]
	v_mov_b64_e32 v[28:29], v[12:13]
	v_mov_b64_e32 v[26:27], v[10:11]
	v_mov_b64_e32 v[24:25], v[8:9]
	v_mov_b64_e32 v[22:23], v[6:7]
	v_mov_b64_e32 v[20:21], v[4:5]
	v_mov_b64_e32 v[18:19], v[2:3]
	v_mov_b64_e32 v[16:17], v[0:1]
	s_waitcnt lgkmcnt(0)
	s_cmp_eq_u32 s29, 0
	s_cbranch_scc0 .Lprio_m2
	s_setprio 1

; template <int MODE>
; __device__ __forceinline__ void qkt(f32x16& p0, f32x16& p1, const int (&ka)[4], const int (&kra)[4], const bf16x8* qr) {
;     ...
;         KRD(kb0[0], ka[0], 0); KRD(kb1[0], ka[0], 8192); KRD(kb0[1], ka[1], 0); KRD(kb1[1], ka[1], 8192);
;         KRD(kb0[2], ka[2], 0); KRD(kb1[2], ka[2], 8192); asm volatile("s_waitcnt lgkmcnt(4)" ::: "memory"); SBAR(); p0 = __builtin_amdgcn_mfma_f32_32x32x16_bf16(kb0[0], qr[0], zz, 0, 0, 0); p1 = __builtin_amdgcn_mfma_f32_32x32x16_bf16(kb1[0], qr[0], zz, 0, 0, 0);
;         KRD(kb0[0], ka[3], 0); KRD(kb1[0], ka[3], 8192); asm volatile("s_waitcnt lgkmcnt(4)" ::: "memory"); SBAR(); p0 = __builtin_amdgcn_mfma_f32_32x32x16_bf16(kb0[1], qr[1], p0, 0, 0, 0); p1 = __builtin_amdgcn_mfma_f32_32x32x16_bf16(kb1[1], qr[1], p1, 0, 0, 0);
;         KRD(kb0[1], ka[0], 128); KRD(kb1[1], ka[0], 8320); asm volatile("s_waitcnt lgkmcnt(4)" ::: "memory"); SBAR(); p0 = __builtin_amdgcn_mfma_f32_32x32x16_bf16(kb0[2], qr[2], p0, 0, 0, 0); p1 = __builtin_amdgcn_mfma_f32_32x32x16_bf16(kb1[2], qr[2], p1, 0, 0, 0);
;         KRD(kb0[2], ka[1], 128); KRD(kb1[2], ka[1], 8320); asm volatile("s_waitcnt lgkmcnt(4)" ::: "memory"); SBAR(); p0 = __builtin_amdgcn_mfma_f32_32x32x16_bf16(kb0[0], qr[3], p0, 0, 0, 0); p1 = __builtin_amdgcn_mfma_f32_32x32x16_bf16(kb1[0], qr[3], p1, 0, 0, 0);
;         KRD(kb0[0], ka[2], 128); KRD(kb1[0], ka[2], 8320); asm volatile("s_waitcnt lgkmcnt(4)" ::: "memory"); SBAR(); p0 = __builtin_amdgcn_mfma_f32_32x32x16_bf16(kb0[1], qr[4], p0, 0, 0, 0); p1 = __builtin_amdgcn_mfma_f32_32x32x16_bf16(kb1[1], qr[4], p1, 0, 0, 0);
;         KRD(kb0[1], ka[3], 128); KRD(kb1[1], ka[3], 8320); asm volatile("s_waitcnt lgkmcnt(4)" ::: "memory"); SBAR(); p0 = __builtin_amdgcn_mfma_f32_32x32x16_bf16(kb0[2], qr[5], p0, 0, 0, 0); p1 = __builtin_amdgcn_mfma_f32_32x32x16_bf16(kb1[2], qr[5], p1, 0, 0, 0);
;         KRD(kb0[2], kra[0], 0); KRD(kb1[2], kra[0], 4096); asm volatile("s_waitcnt lgkmcnt(4)" ::: "memory"); SBAR(); p0 = __builtin_amdgcn_mfma_f32_32x32x16_bf16(kb0[0], qr[6], p0, 0, 0, 0); p1 = __builtin_amdgcn_mfma_f32_32x32x16_bf16(kb1[0], qr[6], p1, 0, 0, 0);
;         KRD(kb0[0], kra[1], 0); KRD(kb1[0], kra[1], 4096); asm volatile("s_waitcnt lgkmcnt(4)" ::: "memory"); SBAR(); p0 = __builtin_amdgcn_mfma_f32_32x32x16_bf16(kb0[1], qr[7], p0, 0, 0, 0); p1 = __builtin_amdgcn_mfma_f32_32x32x16_bf16(kb1[1], qr[7], p1, 0, 0, 0);
.LBB0_285:
	v_and_b32_e32 v210, 63, v76
	v_lshlrev_b32_e32 v17, 4, v210
	s_and_b32 s0, s0, 0x3fffffc0
	v_lshlrev_b32_e32 v16, 3, v210
	v_and_b32_e32 v17, 0xc0, v17
	v_lshlrev_b32_e32 v18, 1, v210
	s_lshl_b32 s0, s0, 2
	v_and_or_b32 v17, v16, 24, v17
	v_and_b32_e32 v18, 32, v18
	v_and_b32_e32 v16, 0x100, v16
	s_add_i32 s23, s0, 0
	v_or3_b32 v16, v17, v18, v16
	v_lshlrev_b32_e32 v211, 4, v204
	v_lshlrev_b32_e32 v17, 4, v76
	s_add_i32 s0, 0, 0x1c000
	v_add_u32_e32 v212, 0, v16
	v_lshl_add_u32 v16, v203, 8, s5
	v_and_b32_e32 v17, 0x70, v17
	v_lshl_add_u32 v18, v203, 7, s0
	v_and_b32_e32 v19, 0x70, v77
	v_or_b32_e32 v20, 32, v211
	v_xad_u32 v215, v20, v17, v16
	v_xad_u32 v216, v20, v19, v18
	v_or_b32_e32 v20, 64, v211
	v_xad_u32 v217, v20, v17, v16
	v_xad_u32 v218, v20, v19, v18
	v_or_b32_e32 v20, 0x60, v211
	v_xad_u32 v213, v211, v17, v16
	v_xad_u32 v214, v211, v19, v18
	v_xad_u32 v219, v20, v17, v16
	v_xad_u32 v220, v20, v19, v18
	ds_read_b128 v[16:19], v213 offset:0
	ds_read_b128 v[20:23], v213 offset:0x2000
	ds_read_b128 v[70:73], v215 offset:0
	ds_read_b128 v[80:83], v215 offset:0x2000
	ds_read_b128 v[84:87], v217 offset:0
	ds_read_b128 v[88:91], v217 offset:0x2000
	s_waitcnt lgkmcnt(4)
	s_add_i32 s23, s23, 0x22000
	v_mov_b32_e32 v1, v0
	v_mov_b32_e32 v2, v0
	v_mov_b32_e32 v3, v0
	v_mov_b32_e32 v4, v0
	v_mov_b32_e32 v5, v0
	v_mov_b32_e32 v6, v0
	v_mov_b32_e32 v7, v0
	v_mov_b32_e32 v8, v0
	v_mov_b32_e32 v9, v0
	v_mov_b32_e32 v10, v0
	v_mov_b32_e32 v11, v0
	v_mov_b32_e32 v12, v0
	v_mov_b32_e32 v13, v0
	v_mov_b32_e32 v14, v0
	v_mov_b32_e32 v15, v0
	s_mov_b32 s42, 3
	s_mov_b32 s43, 1
	v_mfma_f32_32x32x16_bf16 v[32:47], v[16:19], v[96:99], 0
	ds_read_b128 v[92:95], v219 offset:0
	ds_read_b128 v[144:147], v219 offset:0x2000
	s_waitcnt lgkmcnt(4)
	v_mfma_f32_32x32x16_bf16 v[16:31], v[20:23], v[96:99], 0
	v_mfma_f32_32x32x16_bf16 v[32:47], v[70:73], v[100:103], v[32:47]
	ds_read_b128 v[70:73], v213 offset:0x80
	v_mfma_f32_32x32x16_bf16 v[16:31], v[80:83], v[100:103], v[16:31]
	ds_read_b128 v[80:83], v213 offset:0x2080
	s_waitcnt lgkmcnt(4)
	v_mfma_f32_32x32x16_bf16 v[32:47], v[84:87], v[104:107], v[32:47]
	ds_read_b128 v[84:87], v215 offset:0x80
	v_mfma_f32_32x32x16_bf16 v[16:31], v[88:91], v[104:107], v[16:31]
	ds_read_b128 v[88:91], v215 offset:0x2080
	s_waitcnt lgkmcnt(4)
	v_mfma_f32_32x32x16_bf16 v[32:47], v[92:95], v[108:111], v[32:47]
	ds_read_b128 v[92:95], v217 offset:0x80
	v_mfma_f32_32x32x16_bf16 v[16:31], v[144:147], v[108:111], v[16:31]
	ds_read_b128 v[144:147], v217 offset:0x2080
	s_waitcnt lgkmcnt(4)
	v_mfma_f32_32x32x16_bf16 v[32:47], v[70:73], v[112:115], v[32:47]
	ds_read_b128 v[70:73], v219 offset:0x80
	v_mfma_f32_32x32x16_bf16 v[16:31], v[80:83], v[112:115], v[16:31]
	ds_read_b128 v[80:83], v219 offset:0x2080
	s_waitcnt lgkmcnt(4)
	v_mfma_f32_32x32x16_bf16 v[32:47], v[84:87], v[116:119], v[32:47]
	ds_read_b128 v[84:87], v214 offset:0
	v_mfma_f32_32x32x16_bf16 v[16:31], v[88:91], v[116:119], v[16:31]
	ds_read_b128 v[88:91], v214 offset:0x1000
	s_waitcnt lgkmcnt(4)
	v_mfma_f32_32x32x16_bf16 v[32:47], v[92:95], v[120:123], v[32:47]
	ds_read_b128 v[92:95], v216 offset:0
	v_mfma_f32_32x32x16_bf16 v[16:31], v[144:147], v[120:123], v[16:31]
	ds_read_b128 v[144:147], v216 offset:0x1000
	s_waitcnt lgkmcnt(4)
	v_mfma_f32_32x32x16_bf16 v[32:47], v[70:73], v[124:127], v[32:47]
	ds_read_b128 v[70:73], v218 offset:0
	v_mfma_f32_32x32x16_bf16 v[16:31], v[80:83], v[124:127], v[16:31]
	ds_read_b128 v[80:83], v218 offset:0x1000
	s_waitcnt lgkmcnt(4)
	v_mfma_f32_32x32x16_bf16 v[32:47], v[84:87], v[128:131], v[32:47]
	ds_read_b128 v[84:87], v220 offset:0
	v_mfma_f32_32x32x16_bf16 v[16:31], v[88:91], v[128:131], v[16:31]
	ds_read_b128 v[88:91], v220 offset:0x1000
	s_waitcnt lgkmcnt(4)
	v_mfma_f32_32x32x16_bf16 v[32:47], v[92:95], v[136:139], v[32:47]
	s_waitcnt lgkmcnt(2)
	v_mfma_f32_32x32x16_bf16 v[16:31], v[144:147], v[136:139], v[16:31]
	v_mfma_f32_32x32x16_bf16 v[32:47], v[70:73], v[132:135], v[32:47]
	s_waitcnt lgkmcnt(0)
	v_mfma_f32_32x32x16_bf16 v[16:31], v[80:83], v[132:135], v[16:31]
	v_mfma_f32_32x32x16_bf16 v[32:47], v[84:87], v[140:143], v[32:47]
	s_barrier
	v_lshl_add_u32 v222, v203, 2, s23
	s_mov_b32 s45, 0
	s_mov_b32 s44, 0
	s_nop 7
	v_max_f32_e32 v70, v33, v33
	v_max_f32_e32 v71, v32, v32
	v_mfma_f32_32x32x16_bf16 v[16:31], v[88:91], v[140:143], v[16:31]
	v_max_f32_e32 v70, v71, v70
	v_max3_f32 v70, v70, v34, v35
	v_max3_f32 v70, v70, v36, v37
	v_max3_f32 v70, v70, v38, v39
	v_max3_f32 v70, v70, v40, v41
	v_max3_f32 v70, v70, v42, v43
	v_max3_f32 v70, v70, v44, v45
	v_max3_f32 v70, v70, v46, v47
	s_nop 3
	v_max3_f32 v70, v70, v16, v17
	v_max3_f32 v70, v70, v18, v19
	v_max3_f32 v70, v70, v20, v21
	v_max3_f32 v70, v70, v22, v23
	v_max3_f32 v70, v70, v24, v25
	v_max3_f32 v70, v70, v26, v27
	v_max3_f32 v70, v70, v28, v29
	v_max3_f32 v70, v70, v30, v31
	v_mov_b32_e32 v71, v70
	s_nop 1
	v_permlane32_swap_b32_e32 v70, v71
	v_max_f32_e32 v71, v71, v71
	v_max_f32_e32 v70, v70, v70
	v_max_f32_e32 v70, v70, v71
	v_add_f32_e32 v71, 0x46ea6000, v70
	v_cmp_ge_f32_e32 vcc, s1, v71
	s_cmp_eq_u64 vcc, exec
	s_cselect_b64 vcc, -1, 0
	v_max_f32_e32 v70, 0xc6ea6000, v70
	v_cndmask_b32_e32 v221, v70, v193, vcc
	v_mul_f32_e32 v71, 0xbdd53b94, v221
	v_fmamk_f32 v32, v32, 0x3dd53b94, v71
	v_fmamk_f32 v33, v33, 0x3dd53b94, v71
	v_fmamk_f32 v34, v34, 0x3dd53b94, v71
	v_fmamk_f32 v35, v35, 0x3dd53b94, v71
	v_fmamk_f32 v36, v36, 0x3dd53b94, v71
	v_fmamk_f32 v37, v37, 0x3dd53b94, v71
	v_fmamk_f32 v38, v38, 0x3dd53b94, v71
	v_fmamk_f32 v39, v39, 0x3dd53b94, v71
	v_fmamk_f32 v40, v40, 0x3dd53b94, v71
	v_fmamk_f32 v41, v41, 0x3dd53b94, v71
	v_fmamk_f32 v42, v42, 0x3dd53b94, v71
; #define SBAR() __builtin_amdgcn_sched_barrier(0)
; #define SLOAD(k0) SLOADX(sg, k0)
; #define KADDR(slot) do { _Pragma("unroll") for (int i = 0; i < 4; ++i) { ka[i] = kb_[i] + (slot) * SHM_K; kra[i] = krb_[i] + (slot) * SHM_KR; } } while (0)
; __device__ __forceinline__ void finishSM(f32x16& p0, f32x16& p1, float alpha, float& l_reg, bf16x8& pa0, bf16x8& pa1, bf16x8& pa2, bf16x8& pa3) {
;     ...
;     for (int r = 0; r < 16; ++r) p1[r] = __builtin_amdgcn_exp2f(p1[r]);
;     float ps = 0;
; #pragma unroll
;     for (int r = 0; r < 16; ++r) ps += p0[r];
; #pragma unroll
;     for (int r = 0; r < 16; ++r) ps += p1[r];
;     { auto rr = __builtin_amdgcn_permlane32_swap(__float_as_uint(ps), __float_as_uint(ps), false, false);
;       ps = __uint_as_float(rr[0]) + __uint_as_float(rr[1]); }
;     l_reg = l_reg * alpha + ps;
;     ...
;     PK4(p0, 0, pa0); PK4(p0, 8, pa1); PK4(p1, 0, pa2); PK4(p1, 8, pa3);
; template <int MODE> ...
;     ...
;     if (2 < NT) { asm volatile("s_waitcnt vmcnt(0)" ::: "memory"); SWRITEX(sg, 2, 2); } if (3 < NT) SLOAD(3 * 64);
;     __syncthreads();
;     int ks = 1, vp = 0, kw = 0, vw = 3;
;     for (int j = 1; j < NT; ++j) {
;         KADDR(ks); SBAR();
;         if constexpr (MODE != 0) { const bool ap = ACT(j - 1), ac = ACT(j); VFr fa; if (ap) vread<0>(fa, vb0 + vp * SHM_V); if (ac) qkt<MODE>(p0, p1, ka, kra, qr); if (ap) pv_pipe(o, vb0 + vp * SHM_V, fa, pa0, pa1, pa2, pa3); }
	v_fmamk_f32 v43, v43, 0x3dd53b94, v71
	v_fmamk_f32 v44, v44, 0x3dd53b94, v71
	v_fmamk_f32 v45, v45, 0x3dd53b94, v71
	v_fmamk_f32 v46, v46, 0x3dd53b94, v71
	v_fmamk_f32 v47, v47, 0x3dd53b94, v71
	v_fmamk_f32 v16, v16, 0x3dd53b94, v71
	v_fmamk_f32 v17, v17, 0x3dd53b94, v71
	v_fmamk_f32 v18, v18, 0x3dd53b94, v71
	v_fmamk_f32 v19, v19, 0x3dd53b94, v71
	v_fmamk_f32 v20, v20, 0x3dd53b94, v71
	v_fmamk_f32 v21, v21, 0x3dd53b94, v71
	v_fmamk_f32 v22, v22, 0x3dd53b94, v71
	v_fmamk_f32 v23, v23, 0x3dd53b94, v71
	v_fmamk_f32 v24, v24, 0x3dd53b94, v71
	v_fmamk_f32 v25, v25, 0x3dd53b94, v71
	v_fmamk_f32 v26, v26, 0x3dd53b94, v71
	v_fmamk_f32 v27, v27, 0x3dd53b94, v71
	v_fmamk_f32 v28, v28, 0x3dd53b94, v71
	v_fmamk_f32 v29, v29, 0x3dd53b94, v71
	v_fmamk_f32 v30, v30, 0x3dd53b94, v71
	v_fmac_f32_e32 v71, 0x3dd53b94, v31
	v_exp_f32_e32 v31, v32
	v_exp_f32_e32 v32, v33
	v_exp_f32_e32 v33, v34
	v_exp_f32_e32 v34, v35
	v_exp_f32_e32 v35, v36
	v_exp_f32_e32 v36, v37
	v_exp_f32_e32 v37, v38
	v_exp_f32_e32 v38, v39
	v_exp_f32_e32 v39, v40
	v_exp_f32_e32 v40, v41
	v_exp_f32_e32 v41, v42
	v_exp_f32_e32 v42, v43
	v_exp_f32_e32 v43, v44
	v_exp_f32_e32 v44, v45
	v_exp_f32_e32 v45, v46
	v_exp_f32_e32 v46, v47
	v_exp_f32_e32 v47, v71
	v_add_f32_e32 v71, 0, v31
	v_add_f32_e32 v71, v32, v71
	v_add_f32_e32 v71, v33, v71
	v_add_f32_e32 v71, v34, v71
	v_add_f32_e32 v71, v35, v71
	v_add_f32_e32 v71, v36, v71
	v_add_f32_e32 v71, v37, v71
	v_add_f32_e32 v71, v38, v71
	v_add_f32_e32 v71, v39, v71
	v_add_f32_e32 v71, v40, v71
	v_add_f32_e32 v71, v41, v71
	v_add_f32_e32 v71, v42, v71
	v_exp_f32_e32 v16, v16
	v_add_f32_e32 v71, v43, v71
	v_add_f32_e32 v71, v44, v71
	v_exp_f32_e32 v17, v17
	v_add_f32_e32 v71, v45, v71
	v_exp_f32_e32 v18, v18
	v_add_f32_e32 v71, v46, v71
	s_add_i32 s0, 0, 0x18000
	v_exp_f32_e32 v19, v19
	v_add_f32_e32 v71, v16, v71
	v_cvt_pk_bf16_f32 v164, v31, v32
	v_cvt_pk_bf16_f32 v165, v33, v34
	v_cvt_pk_bf16_f32 v166, v35, v36
	v_cvt_pk_bf16_f32 v167, v37, v38
	v_cvt_pk_bf16_f32 v168, v39, v40
	v_cvt_pk_bf16_f32 v169, v41, v42
	v_cvt_pk_bf16_f32 v170, v43, v44
	v_cvt_pk_bf16_f32 v171, v45, v46
	v_cvt_pk_bf16_f32 v172, v16, v17
	v_add_u32_e32 v16, s0, v207
	v_exp_f32_e32 v20, v20
	v_exp_f32_e32 v21, v21
	v_exp_f32_e32 v22, v22
	v_exp_f32_e32 v23, v23
	v_exp_f32_e32 v24, v24
	v_exp_f32_e32 v25, v25
	v_exp_f32_e32 v26, v26
	v_exp_f32_e32 v27, v27
	v_exp_f32_e32 v28, v28
	v_exp_f32_e32 v29, v29
	v_exp_f32_e32 v30, v30
	v_cvt_pk_bf16_f32 v173, v18, v19
	v_cvt_pk_bf16_f32 v174, v20, v21
	v_cvt_pk_bf16_f32 v175, v22, v23
	v_cvt_pk_bf16_f32 v176, v24, v25
	v_cvt_pk_bf16_f32 v177, v26, v27
	v_cvt_pk_bf16_f32 v178, v28, v29
	v_cvt_pk_bf16_f32 v179, v30, v47
	s_waitcnt vmcnt(0)
	s_waitcnt vmcnt(4)
	ds_write_b128 v74, v[48:51] offset:32768
	s_waitcnt vmcnt(3)
	ds_write_b128 v75, v[60:63] offset:32768
	s_waitcnt vmcnt(2)
	ds_write_b128 v16, v[52:55]
	v_add_u32_e32 v16, s0, v208
	v_add_f32_e32 v71, v17, v71
	s_waitcnt vmcnt(1)
	ds_write_b128 v16, v[56:59]
	v_add_u32_e32 v16, 0x20000, v78
	v_add_f32_e32 v71, v18, v71
	s_waitcnt vmcnt(0)
	ds_write_b128 v16, v[64:67]
	v_lshlrev_b64 v[16:17], 1, v[68:69]
	s_and_b64 s[4:5], s[8:9], exec
	v_add_f32_e32 v71, v19, v71
	v_lshl_add_u64 v[18:19], s[6:7], 0, v[16:17]
	s_movk_i32 s0, 0x6000
	s_cselect_b32 s4, s84, 0x180000
	v_add_co_u32_e64 v18, s[6:7], s0, v18
	s_add_u32 s4, s18, s4
	v_add_f32_e32 v71, v20, v71
	v_addc_co_u32_e64 v19, s[6:7], 0, v19, s[6:7]
	s_addc_u32 s5, s19, 0
	v_add_f32_e32 v71, v21, v71
	global_load_dwordx4 v[144:147], v[18:19], off
	v_lshl_add_u64 v[18:19], v[182:183], 1, s[4:5]
	v_lshl_add_u64 v[20:21], v[180:181], 1, s[4:5]
	global_load_dwordx4 v[148:151], v[18:19], off
	global_load_dwordx4 v[152:155], v[20:21], off
	global_load_dwordx4 v[160:163], v[18:19], off offset:256
	global_load_dwordx4 v[156:159], v[20:21], off offset:256
	v_add_f32_e32 v71, v22, v71
	v_add_f32_e32 v71, v23, v71
	v_add_f32_e32 v71, v24, v71
	v_add_f32_e32 v71, v25, v71
	v_add_f32_e32 v71, v26, v71
	v_add_f32_e32 v71, v27, v71
	v_sub_f32_e32 v19, 0xc6ea6000, v70
	v_add_f32_e32 v71, v28, v71
	v_mul_f32_e32 v19, 0x3dd53b94, v19
	v_add_f32_e32 v71, v29, v71
	v_exp_f32_e32 v19, v19
	v_add_f32_e32 v71, v30, v71
	v_add_f32_e32 v71, v47, v71
	s_and_b64 s[4:5], s[8:9], exec
	v_mov_b32_e32 v72, v71
	s_cselect_b32 s33, 10, 12
	s_add_i32 s40, s39, -1
	v_permlane32_swap_b32_e32 v71, v72
	v_mul_f32_e32 v19, 0, v19
	s_add_u32 s4, s34, s20
	v_add_f32_e32 v18, v71, v72
	v_cndmask_b32_e64 v19, v19, 0, vcc
	s_addc_u32 s5, s35, s21
	v_add_f32_e32 v223, v18, v19
	v_lshl_add_u64 v[184:185], s[4:5], 0, v[16:17]
	v_mov_b64_e32 v[62:63], v[14:15]
	v_mov_b64_e32 v[46:47], v[14:15]
	v_mov_b64_e32 v[30:31], v[14:15]
	v_permlane32_swap_b32_e32 v164, v166
	v_permlane32_swap_b32_e32 v165, v167
	v_permlane32_swap_b32_e32 v168, v170
	v_permlane32_swap_b32_e32 v169, v171
	v_permlane32_swap_b32_e32 v172, v174
	v_permlane32_swap_b32_e32 v173, v175
	v_permlane32_swap_b32_e32 v176, v178
	v_permlane32_swap_b32_e32 v177, v179
	s_mov_b32 s0, 0
	v_cmp_gt_u32_e64 s[6:7], 32, v210
	s_mov_b64 s[20:21], 0x100
	v_mov_b64_e32 v[60:61], v[12:13]
	v_mov_b64_e32 v[58:59], v[10:11]
	v_mov_b64_e32 v[56:57], v[8:9]
	v_mov_b64_e32 v[54:55], v[6:7]
	v_mov_b64_e32 v[52:53], v[4:5]
	v_mov_b64_e32 v[50:51], v[2:3]
	v_mov_b64_e32 v[48:49], v[0:1]
	v_mov_b64_e32 v[44:45], v[12:13]
	v_mov_b64_e32 v[42:43], v[10:11]
	v_mov_b64_e32 v[40:41], v[8:9]
	v_mov_b64_e32 v[38:39], v[6:7]
	v_mov_b64_e32 v[36:37], v[4:5]
	v_mov_b64_e32 v[34:35], v[2:3]
	v_mov_b64_e32 v[32:33], v[0:1]
	v_mov_b64_e32 v[28:29], v[12:13]
	v_mov_b64_e32 v[26:27], v[10:11]
	v_mov_b64_e32 v[24:25], v[8:9]
	v_mov_b64_e32 v[22:23], v[6:7]
	v_mov_b64_e32 v[20:21], v[4:5]
	v_mov_b64_e32 v[18:19], v[2:3]
	v_mov_b64_e32 v[16:17], v[0:1]
	s_lshl_b32 s4, s43, 14
	s_lshl_b32 s5, s43, 13
	v_add_u32_e32 v248, s4, v213
	v_add_u32_e32 v249, s5, v214
	v_add_u32_e32 v250, s4, v215
	v_add_u32_e32 v251, s5, v216
	v_add_u32_e32 v252, s4, v217
	v_add_u32_e32 v253, s5, v218
	v_add_u32_e32 v188, s4, v219
	v_add_u32_e32 v191, s5, v220
	ds_read_b128 v[192:195], v248 offset:0x0
	ds_read_b128 v[196:199], v248 offset:0x2000
	ds_read_b128 v[224:227], v250 offset:0x0
	ds_read_b128 v[228:231], v250 offset:0x2000
	ds_read_b128 v[232:235], v252 offset:0x0
	ds_read_b128 v[236:239], v252 offset:0x2000
	ds_read_b128 v[240:243], v188 offset:0x0
	ds_read_b128 v[244:247], v188 offset:0x2000
	s_waitcnt lgkmcnt(8)
	s_cmp_eq_u32 s22, 0
	s_cbranch_scc0 .Lprio_m0
	s_setprio 1
